# EpiSwiglu epilogues (GU1, GU2): silu(g*rs)*(up*rs) math as packed f32 ops on accumulator pairs, same ops and order per element, no pairing movs
# speedup vs baseline: 1.0080x; 1.0080x over previous
; __device__ __forceinline__ unsigned pk2(float lo, float hi) { return pg8::cvt_pk_bf16(lo, hi); }
;     __device__ __forceinline__ void operator()(const f32x4 (&acc)[2][2][4][2], const Unit& u, int wr, int wc, int fr, int fq) const {
;         bf16_t* O = O_; const float* rss = rss_; asm volatile("" : "+s"(O), "+s"(rss));
;         const int row0 = u.pm * 256 + wr * 64 + fr, col0 = u.pn * 128 + wc * 32 + 8 * fq;
;         float rsv[2][4];
;         { f32x4 pp[2][4];
; #pragma unroll
;           for (int ai = 0; ai < 2; ++ai)
; #pragma unroll
;             for (int m = 0; m < 4; ++m) pp[ai][m] = *(const f32x4*)(rss + (size_t)(row0 + ai * 128 + m * 16) * 4);
; #pragma unroll
;           for (int ai = 0; ai < 2; ++ai)
; #pragma unroll
;             for (int m = 0; m < 4; ++m) rsv[ai][m] = __builtin_amdgcn_rsqf(((pp[ai][m][0] + pp[ai][m][1]) + (pp[ai][m][2] + pp[ai][m][3])) * (1.0f / D) + EPS); }
; #pragma unroll
;         for (int ai = 0; ai < 2; ++ai)
; #pragma unroll
;             for (int m = 0; m < 4; ++m) {
;                 bf16_t* rowp = O + (size_t)(row0 + ai * 128 + m * 16) * FF + col0;
;                 const float rs = rsv[ai][m];
;                 float v[8];
; #pragma unroll
;                 for (int n = 0; n < 2; ++n)
; #pragma unroll
;                     for (int j = 0; j < 4; ++j) { const float g = acc[ai][0][m][n][j] * rs, up = acc[ai][1][m][n][j] * rs; v[n * 4 + j] = g * __builtin_amdgcn_rcpf(1.0f + __expf(-g)) * up; }
;                 u32x4v w; w.x = pk2(v[0], v[1]); w.y = pk2(v[2], v[3]); w.z = pk2(v[4], v[5]); w.w = pk2(v[6], v[7]);
;                 *(u32x4v*)rowp = w;
.LBB0_322:
	v_readlane_b32 s58, v250, 28
	v_readlane_b32 s70, v251, 4
	v_lshl_add_u32 v180, s56, 8, v147
	v_readlane_b32 s59, v250, 29
	v_readlane_b32 s71, v251, 5
	v_ashrrev_i32_e32 v181, 31, v180
	v_or_b32_e32 v176, 16, v180
	v_lshl_add_u64 v[140:141], v[180:181], 4, s[58:59]
	global_load_dwordx4 v[182:185], v[140:141], off
	v_ashrrev_i32_e32 v177, 31, v176
	v_or_b32_e32 v172, 32, v180
	v_lshl_add_u64 v[140:141], v[176:177], 4, s[58:59]
	v_ashrrev_i32_e32 v173, 31, v172
	v_or_b32_e32 v168, 48, v180
	global_load_dwordx4 v[186:189], v[140:141], off
	v_lshl_add_u64 v[140:141], v[172:173], 4, s[58:59]
	v_ashrrev_i32_e32 v169, 31, v168
	v_add_u32_e32 v154, 0x80, v180
	global_load_dwordx4 v[190:193], v[140:141], off
	v_lshl_add_u64 v[140:141], v[168:169], 4, s[58:59]
	v_ashrrev_i32_e32 v155, 31, v154
	v_add_u32_e32 v150, 0x90, v180
	global_load_dwordx4 v[194:197], v[140:141], off
	v_lshl_add_u64 v[140:141], v[154:155], 4, s[58:59]
	v_ashrrev_i32_e32 v151, 31, v150
	v_add_u32_e32 v142, 0xa0, v180
	global_load_dwordx4 v[198:201], v[140:141], off
	v_lshl_add_u64 v[140:141], v[150:151], 4, s[58:59]
	v_ashrrev_i32_e32 v143, 31, v142
	global_load_dwordx4 v[202:205], v[140:141], off
	v_lshl_add_u64 v[140:141], v[142:143], 4, s[58:59]
	global_load_dwordx4 v[210:213], v[140:141], off
	v_add_u32_e32 v140, 0xb0, v180
	v_ashrrev_i32_e32 v141, 31, v140
	v_lshl_add_u64 v[144:145], v[140:141], 4, s[58:59]
	global_load_dwordx4 v[214:217], v[144:145], off
	s_and_b64 vcc, exec, s[40:41]
	s_waitcnt vmcnt(0) lgkmcnt(0)
	v_add_f32_e32 v182, v183, v182
	v_add_f32_e32 v186, v187, v186
	v_add_f32_e32 v190, v191, v190
	v_add_f32_e32 v194, v195, v194
	v_add_f32_e32 v198, v199, v198
	v_add_f32_e32 v202, v203, v202
	v_add_f32_e32 v210, v211, v210
	v_add_f32_e32 v214, v215, v214
	v_add_f32_e32 v184, v184, v185
	v_add_f32_e32 v188, v188, v189
	v_add_f32_e32 v192, v192, v193
	v_add_f32_e32 v196, v196, v197
	v_add_f32_e32 v200, v200, v201
	v_add_f32_e32 v204, v204, v205
	v_add_f32_e32 v212, v212, v213
	v_add_f32_e32 v216, v216, v217
	v_add_f32_e32 v182, v182, v184
	v_add_f32_e32 v186, v186, v188
	v_add_f32_e32 v190, v190, v192
	v_add_f32_e32 v194, v194, v196
	v_add_f32_e32 v198, v198, v200
	v_add_f32_e32 v202, v202, v204
	v_add_f32_e32 v210, v210, v212
	v_add_f32_e32 v214, v214, v216
	v_fmamk_f32 v182, v182, 0x3a800000, v159
	v_fmamk_f32 v186, v186, 0x3a800000, v159
	v_fmamk_f32 v190, v190, 0x3a800000, v159
	v_fmamk_f32 v194, v194, 0x3a800000, v159
	v_fmamk_f32 v198, v198, 0x3a800000, v159
	v_fmamk_f32 v202, v202, 0x3a800000, v159
	v_fmamk_f32 v210, v210, 0x3a800000, v159
	v_fmamk_f32 v214, v214, 0x3a800000, v159
	v_rsq_f32_e32 v182, v182
	v_rsq_f32_e32 v178, v186
	v_rsq_f32_e32 v174, v190
	v_rsq_f32_e32 v170, v194
	v_rsq_f32_e32 v156, v198
	v_rsq_f32_e32 v152, v202
	v_rsq_f32_e32 v148, v210
	v_rsq_f32_e32 v146, v214
	v_mov_b32_e32 v214, 0xbfb8aa3b
	v_mov_b32_e32 v216, 1.0
	v_lshl_or_b32 v144, s55, 7, v153
	v_ashrrev_i32_e32 v145, 31, v144
	v_lshl_add_u64 v[144:145], v[144:145], 1, s[70:71]
	s_mov_b64 s[70:71], -1
	v_pk_mul_f32 v[122:123], v[122:123], v[182:183] op_sel_hi:[1,0]
	v_pk_mul_f32 v[124:125], v[124:125], v[182:183] op_sel_hi:[1,0]
	v_pk_mul_f32 v[114:115], v[114:115], v[182:183] op_sel_hi:[1,0]
	v_pk_mul_f32 v[116:117], v[116:117], v[182:183] op_sel_hi:[1,0]
	v_pk_mul_f32 v[186:187], v[122:123], v[214:215] op_sel_hi:[1,0]
	v_pk_mul_f32 v[188:189], v[124:125], v[214:215] op_sel_hi:[1,0]
	v_pk_mul_f32 v[190:191], v[114:115], v[214:215] op_sel_hi:[1,0]
	v_pk_mul_f32 v[192:193], v[116:117], v[214:215] op_sel_hi:[1,0]
	v_pk_mul_f32 v[126:127], v[126:127], v[182:183] op_sel_hi:[1,0]
	v_pk_mul_f32 v[128:129], v[128:129], v[182:183] op_sel_hi:[1,0]
	v_pk_mul_f32 v[118:119], v[118:119], v[182:183] op_sel_hi:[1,0]
	v_pk_mul_f32 v[120:121], v[120:121], v[182:183] op_sel_hi:[1,0]
	v_exp_f32_e32 v186, v186
	v_exp_f32_e32 v187, v187
	v_exp_f32_e32 v188, v188
	v_exp_f32_e32 v189, v189
	v_exp_f32_e32 v190, v190
	v_exp_f32_e32 v191, v191
	v_exp_f32_e32 v192, v192
	v_exp_f32_e32 v193, v193
	v_pk_add_f32 v[186:187], v[186:187], v[216:217] op_sel_hi:[1,0]
	v_pk_add_f32 v[188:189], v[188:189], v[216:217] op_sel_hi:[1,0]
	v_pk_add_f32 v[190:191], v[190:191], v[216:217] op_sel_hi:[1,0]
	v_pk_add_f32 v[192:193], v[192:193], v[216:217] op_sel_hi:[1,0]
	v_rcp_f32_e32 v186, v186
	v_rcp_f32_e32 v187, v187
	v_rcp_f32_e32 v188, v188
	v_rcp_f32_e32 v189, v189
	v_rcp_f32_e32 v190, v190
	v_rcp_f32_e32 v191, v191
	v_rcp_f32_e32 v192, v192
	v_rcp_f32_e32 v193, v193
	v_pk_mul_f32 v[186:187], v[122:123], v[186:187]
	v_pk_mul_f32 v[188:189], v[124:125], v[188:189]
	v_pk_mul_f32 v[190:191], v[114:115], v[190:191]
	v_pk_mul_f32 v[192:193], v[116:117], v[192:193]
	v_pk_mul_f32 v[186:187], v[126:127], v[186:187]
	v_pk_mul_f32 v[188:189], v[128:129], v[188:189]
	v_pk_mul_f32 v[190:191], v[118:119], v[190:191]
	v_pk_mul_f32 v[192:193], v[120:121], v[192:193]
	v_mad_i64_i32 v[118:119], s[56:57], v180, s85, v[144:145]
	v_cvt_pk_bf16_f32 v114, v186, v187
	v_cvt_pk_bf16_f32 v115, v188, v189
	v_cvt_pk_bf16_f32 v116, v190, v191
	v_cvt_pk_bf16_f32 v117, v192, v193
	global_store_dwordx4 v[118:119], v[114:117], off
	v_pk_mul_f32 v[106:107], v[106:107], v[178:179] op_sel_hi:[1,0]
	v_pk_mul_f32 v[108:109], v[108:109], v[178:179] op_sel_hi:[1,0]
	v_pk_mul_f32 v[98:99], v[98:99], v[178:179] op_sel_hi:[1,0]
	v_pk_mul_f32 v[100:101], v[100:101], v[178:179] op_sel_hi:[1,0]
	v_pk_mul_f32 v[122:123], v[106:107], v[214:215] op_sel_hi:[1,0]
	v_pk_mul_f32 v[124:125], v[108:109], v[214:215] op_sel_hi:[1,0]
	v_pk_mul_f32 v[126:127], v[98:99], v[214:215] op_sel_hi:[1,0]
	v_pk_mul_f32 v[128:129], v[100:101], v[214:215] op_sel_hi:[1,0]
; __device__ __forceinline__ unsigned pk2(float lo, float hi) { return pg8::cvt_pk_bf16(lo, hi); }
;     __device__ __forceinline__ void operator()(const f32x4 (&acc)[2][2][4][2], const Unit& u, int wr, int wc, int fr, int fq) const {
;     ...
; #pragma unroll
;         for (int ai = 0; ai < 2; ++ai)
; #pragma unroll
;             for (int m = 0; m < 4; ++m) {
;                 bf16_t* rowp = O + (size_t)(row0 + ai * 128 + m * 16) * FF + col0;
;                 const float rs = rsv[ai][m];
;                 float v[8];
; #pragma unroll
;                 for (int n = 0; n < 2; ++n)
; #pragma unroll
;                     for (int j = 0; j < 4; ++j) { const float g = acc[ai][0][m][n][j] * rs, up = acc[ai][1][m][n][j] * rs; v[n * 4 + j] = g * __builtin_amdgcn_rcpf(1.0f + __expf(-g)) * up; }
;                 u32x4v w; w.x = pk2(v[0], v[1]); w.y = pk2(v[2], v[3]); w.z = pk2(v[4], v[5]); w.w = pk2(v[6], v[7]);
;                 *(u32x4v*)rowp = w;
	v_pk_mul_f32 v[110:111], v[110:111], v[178:179] op_sel_hi:[1,0]
	v_pk_mul_f32 v[112:113], v[112:113], v[178:179] op_sel_hi:[1,0]
	v_pk_mul_f32 v[102:103], v[102:103], v[178:179] op_sel_hi:[1,0]
	v_pk_mul_f32 v[104:105], v[104:105], v[178:179] op_sel_hi:[1,0]
	v_exp_f32_e32 v122, v122
	v_exp_f32_e32 v123, v123
	v_exp_f32_e32 v124, v124
	v_exp_f32_e32 v125, v125
	v_exp_f32_e32 v126, v126
	v_exp_f32_e32 v127, v127
	v_exp_f32_e32 v128, v128
	v_exp_f32_e32 v129, v129
	v_pk_add_f32 v[122:123], v[122:123], v[216:217] op_sel_hi:[1,0]
	v_pk_add_f32 v[124:125], v[124:125], v[216:217] op_sel_hi:[1,0]
	v_pk_add_f32 v[126:127], v[126:127], v[216:217] op_sel_hi:[1,0]
	v_pk_add_f32 v[128:129], v[128:129], v[216:217] op_sel_hi:[1,0]
	v_rcp_f32_e32 v122, v122
	v_rcp_f32_e32 v123, v123
	v_rcp_f32_e32 v124, v124
	v_rcp_f32_e32 v125, v125
	v_rcp_f32_e32 v126, v126
	v_rcp_f32_e32 v127, v127
	v_rcp_f32_e32 v128, v128
	v_rcp_f32_e32 v129, v129
	v_pk_mul_f32 v[122:123], v[106:107], v[122:123]
	v_pk_mul_f32 v[124:125], v[108:109], v[124:125]
	v_pk_mul_f32 v[126:127], v[98:99], v[126:127]
	v_pk_mul_f32 v[128:129], v[100:101], v[128:129]
	v_pk_mul_f32 v[122:123], v[110:111], v[122:123]
	v_pk_mul_f32 v[124:125], v[112:113], v[124:125]
	v_pk_mul_f32 v[126:127], v[102:103], v[126:127]
	v_pk_mul_f32 v[128:129], v[104:105], v[128:129]
	v_mad_i64_i32 v[102:103], s[56:57], v176, s85, v[144:145]
	v_cvt_pk_bf16_f32 v98, v122, v123
	v_cvt_pk_bf16_f32 v99, v124, v125
	v_cvt_pk_bf16_f32 v100, v126, v127
	v_cvt_pk_bf16_f32 v101, v128, v129
	global_store_dwordx4 v[102:103], v[98:101], off
	v_pk_mul_f32 v[90:91], v[90:91], v[174:175] op_sel_hi:[1,0]
	v_pk_mul_f32 v[92:93], v[92:93], v[174:175] op_sel_hi:[1,0]
	v_pk_mul_f32 v[82:83], v[82:83], v[174:175] op_sel_hi:[1,0]
	v_pk_mul_f32 v[84:85], v[84:85], v[174:175] op_sel_hi:[1,0]
	v_pk_mul_f32 v[106:107], v[90:91], v[214:215] op_sel_hi:[1,0]
	v_pk_mul_f32 v[108:109], v[92:93], v[214:215] op_sel_hi:[1,0]
	v_pk_mul_f32 v[110:111], v[82:83], v[214:215] op_sel_hi:[1,0]
	v_pk_mul_f32 v[112:113], v[84:85], v[214:215] op_sel_hi:[1,0]
	v_pk_mul_f32 v[94:95], v[94:95], v[174:175] op_sel_hi:[1,0]
	v_pk_mul_f32 v[96:97], v[96:97], v[174:175] op_sel_hi:[1,0]
	v_pk_mul_f32 v[86:87], v[86:87], v[174:175] op_sel_hi:[1,0]
	v_pk_mul_f32 v[88:89], v[88:89], v[174:175] op_sel_hi:[1,0]
	v_exp_f32_e32 v106, v106
	v_exp_f32_e32 v107, v107
	v_exp_f32_e32 v108, v108
	v_exp_f32_e32 v109, v109
	v_exp_f32_e32 v110, v110
	v_exp_f32_e32 v111, v111
	v_exp_f32_e32 v112, v112
	v_exp_f32_e32 v113, v113
	v_pk_add_f32 v[106:107], v[106:107], v[216:217] op_sel_hi:[1,0]
	v_pk_add_f32 v[108:109], v[108:109], v[216:217] op_sel_hi:[1,0]
	v_pk_add_f32 v[110:111], v[110:111], v[216:217] op_sel_hi:[1,0]
	v_pk_add_f32 v[112:113], v[112:113], v[216:217] op_sel_hi:[1,0]
	v_rcp_f32_e32 v106, v106
	v_rcp_f32_e32 v107, v107
	v_rcp_f32_e32 v108, v108
	v_rcp_f32_e32 v109, v109
	v_rcp_f32_e32 v110, v110
	v_rcp_f32_e32 v111, v111
	v_rcp_f32_e32 v112, v112
	v_rcp_f32_e32 v113, v113
	v_pk_mul_f32 v[106:107], v[90:91], v[106:107]
	v_pk_mul_f32 v[108:109], v[92:93], v[108:109]
	v_pk_mul_f32 v[110:111], v[82:83], v[110:111]
	v_pk_mul_f32 v[112:113], v[84:85], v[112:113]
	v_pk_mul_f32 v[106:107], v[94:95], v[106:107]
	v_pk_mul_f32 v[108:109], v[96:97], v[108:109]
	v_pk_mul_f32 v[110:111], v[86:87], v[110:111]
	v_pk_mul_f32 v[112:113], v[88:89], v[112:113]
	v_mad_i64_i32 v[86:87], s[56:57], v172, s85, v[144:145]
	v_cvt_pk_bf16_f32 v82, v106, v107
	v_cvt_pk_bf16_f32 v83, v108, v109
	v_cvt_pk_bf16_f32 v84, v110, v111
	v_cvt_pk_bf16_f32 v85, v112, v113
	global_store_dwordx4 v[86:87], v[82:85], off
	v_pk_mul_f32 v[74:75], v[74:75], v[170:171] op_sel_hi:[1,0]
	v_pk_mul_f32 v[76:77], v[76:77], v[170:171] op_sel_hi:[1,0]
	v_pk_mul_f32 v[66:67], v[66:67], v[170:171] op_sel_hi:[1,0]
	v_pk_mul_f32 v[68:69], v[68:69], v[170:171] op_sel_hi:[1,0]
	v_pk_mul_f32 v[90:91], v[74:75], v[214:215] op_sel_hi:[1,0]
	v_pk_mul_f32 v[92:93], v[76:77], v[214:215] op_sel_hi:[1,0]
	v_pk_mul_f32 v[94:95], v[66:67], v[214:215] op_sel_hi:[1,0]
	v_pk_mul_f32 v[96:97], v[68:69], v[214:215] op_sel_hi:[1,0]
	v_pk_mul_f32 v[78:79], v[78:79], v[170:171] op_sel_hi:[1,0]
	v_pk_mul_f32 v[80:81], v[80:81], v[170:171] op_sel_hi:[1,0]
	v_pk_mul_f32 v[70:71], v[70:71], v[170:171] op_sel_hi:[1,0]
	v_pk_mul_f32 v[72:73], v[72:73], v[170:171] op_sel_hi:[1,0]
	v_exp_f32_e32 v90, v90
	v_exp_f32_e32 v91, v91
	v_exp_f32_e32 v92, v92
	v_exp_f32_e32 v93, v93
	v_exp_f32_e32 v94, v94
	v_exp_f32_e32 v95, v95
	v_exp_f32_e32 v96, v96
	v_exp_f32_e32 v97, v97
	v_pk_add_f32 v[90:91], v[90:91], v[216:217] op_sel_hi:[1,0]
	v_pk_add_f32 v[92:93], v[92:93], v[216:217] op_sel_hi:[1,0]
	v_pk_add_f32 v[94:95], v[94:95], v[216:217] op_sel_hi:[1,0]
	v_pk_add_f32 v[96:97], v[96:97], v[216:217] op_sel_hi:[1,0]
	v_rcp_f32_e32 v90, v90
	v_rcp_f32_e32 v91, v91
	v_rcp_f32_e32 v92, v92
	v_rcp_f32_e32 v93, v93
	v_rcp_f32_e32 v94, v94
	v_rcp_f32_e32 v95, v95
	v_rcp_f32_e32 v96, v96
	v_rcp_f32_e32 v97, v97
	v_pk_mul_f32 v[90:91], v[74:75], v[90:91]
	v_pk_mul_f32 v[92:93], v[76:77], v[92:93]
	v_pk_mul_f32 v[94:95], v[66:67], v[94:95]
	v_pk_mul_f32 v[96:97], v[68:69], v[96:97]
	v_pk_mul_f32 v[90:91], v[78:79], v[90:91]
	v_pk_mul_f32 v[92:93], v[80:81], v[92:93]
	v_pk_mul_f32 v[94:95], v[70:71], v[94:95]
	v_pk_mul_f32 v[96:97], v[72:73], v[96:97]
	v_mad_i64_i32 v[70:71], s[56:57], v168, s85, v[144:145]
	v_cvt_pk_bf16_f32 v66, v90, v91
	v_cvt_pk_bf16_f32 v67, v92, v93
	v_cvt_pk_bf16_f32 v68, v94, v95
	v_cvt_pk_bf16_f32 v69, v96, v97
	global_store_dwordx4 v[70:71], v[66:69], off
	v_pk_mul_f32 v[58:59], v[58:59], v[156:157] op_sel_hi:[1,0]
; __device__ __forceinline__ unsigned pk2(float lo, float hi) { return pg8::cvt_pk_bf16(lo, hi); }
;     __device__ __forceinline__ void operator()(const f32x4 (&acc)[2][2][4][2], const Unit& u, int wr, int wc, int fr, int fq) const {
;     ...
; #pragma unroll
;         for (int ai = 0; ai < 2; ++ai)
; #pragma unroll
;             for (int m = 0; m < 4; ++m) {
;                 bf16_t* rowp = O + (size_t)(row0 + ai * 128 + m * 16) * FF + col0;
;                 const float rs = rsv[ai][m];
;                 float v[8];
; #pragma unroll
;                 for (int n = 0; n < 2; ++n)
; #pragma unroll
;                     for (int j = 0; j < 4; ++j) { const float g = acc[ai][0][m][n][j] * rs, up = acc[ai][1][m][n][j] * rs; v[n * 4 + j] = g * __builtin_amdgcn_rcpf(1.0f + __expf(-g)) * up; }
;                 u32x4v w; w.x = pk2(v[0], v[1]); w.y = pk2(v[2], v[3]); w.z = pk2(v[4], v[5]); w.w = pk2(v[6], v[7]);
;                 *(u32x4v*)rowp = w;
	v_pk_mul_f32 v[60:61], v[60:61], v[156:157] op_sel_hi:[1,0]
	v_pk_mul_f32 v[50:51], v[50:51], v[156:157] op_sel_hi:[1,0]
	v_pk_mul_f32 v[52:53], v[52:53], v[156:157] op_sel_hi:[1,0]
	v_pk_mul_f32 v[74:75], v[58:59], v[214:215] op_sel_hi:[1,0]
	v_pk_mul_f32 v[76:77], v[60:61], v[214:215] op_sel_hi:[1,0]
	v_pk_mul_f32 v[78:79], v[50:51], v[214:215] op_sel_hi:[1,0]
	v_pk_mul_f32 v[80:81], v[52:53], v[214:215] op_sel_hi:[1,0]
	v_pk_mul_f32 v[62:63], v[62:63], v[156:157] op_sel_hi:[1,0]
	v_pk_mul_f32 v[64:65], v[64:65], v[156:157] op_sel_hi:[1,0]
	v_pk_mul_f32 v[54:55], v[54:55], v[156:157] op_sel_hi:[1,0]
	v_pk_mul_f32 v[56:57], v[56:57], v[156:157] op_sel_hi:[1,0]
	v_exp_f32_e32 v74, v74
	v_exp_f32_e32 v75, v75
	v_exp_f32_e32 v76, v76
	v_exp_f32_e32 v77, v77
	v_exp_f32_e32 v78, v78
	v_exp_f32_e32 v79, v79
	v_exp_f32_e32 v80, v80
	v_exp_f32_e32 v81, v81
	v_pk_add_f32 v[74:75], v[74:75], v[216:217] op_sel_hi:[1,0]
	v_pk_add_f32 v[76:77], v[76:77], v[216:217] op_sel_hi:[1,0]
	v_pk_add_f32 v[78:79], v[78:79], v[216:217] op_sel_hi:[1,0]
	v_pk_add_f32 v[80:81], v[80:81], v[216:217] op_sel_hi:[1,0]
	v_rcp_f32_e32 v74, v74
	v_rcp_f32_e32 v75, v75
	v_rcp_f32_e32 v76, v76
	v_rcp_f32_e32 v77, v77
	v_rcp_f32_e32 v78, v78
	v_rcp_f32_e32 v79, v79
	v_rcp_f32_e32 v80, v80
	v_rcp_f32_e32 v81, v81
	v_pk_mul_f32 v[74:75], v[58:59], v[74:75]
	v_pk_mul_f32 v[76:77], v[60:61], v[76:77]
	v_pk_mul_f32 v[78:79], v[50:51], v[78:79]
	v_pk_mul_f32 v[80:81], v[52:53], v[80:81]
	v_pk_mul_f32 v[74:75], v[62:63], v[74:75]
	v_pk_mul_f32 v[76:77], v[64:65], v[76:77]
	v_pk_mul_f32 v[78:79], v[54:55], v[78:79]
	v_pk_mul_f32 v[80:81], v[56:57], v[80:81]
	v_mad_i64_i32 v[54:55], s[56:57], v154, s85, v[144:145]
	v_cvt_pk_bf16_f32 v50, v74, v75
	v_cvt_pk_bf16_f32 v51, v76, v77
	v_cvt_pk_bf16_f32 v52, v78, v79
	v_cvt_pk_bf16_f32 v53, v80, v81
	global_store_dwordx4 v[54:55], v[50:53], off
	v_pk_mul_f32 v[42:43], v[42:43], v[152:153] op_sel_hi:[1,0]
	v_pk_mul_f32 v[44:45], v[44:45], v[152:153] op_sel_hi:[1,0]
	v_pk_mul_f32 v[34:35], v[34:35], v[152:153] op_sel_hi:[1,0]
	v_pk_mul_f32 v[36:37], v[36:37], v[152:153] op_sel_hi:[1,0]
	v_pk_mul_f32 v[58:59], v[42:43], v[214:215] op_sel_hi:[1,0]
	v_pk_mul_f32 v[60:61], v[44:45], v[214:215] op_sel_hi:[1,0]
	v_pk_mul_f32 v[62:63], v[34:35], v[214:215] op_sel_hi:[1,0]
	v_pk_mul_f32 v[64:65], v[36:37], v[214:215] op_sel_hi:[1,0]
	v_pk_mul_f32 v[46:47], v[46:47], v[152:153] op_sel_hi:[1,0]
	v_pk_mul_f32 v[48:49], v[48:49], v[152:153] op_sel_hi:[1,0]
	v_pk_mul_f32 v[38:39], v[38:39], v[152:153] op_sel_hi:[1,0]
	v_pk_mul_f32 v[40:41], v[40:41], v[152:153] op_sel_hi:[1,0]
	v_exp_f32_e32 v58, v58
	v_exp_f32_e32 v59, v59
	v_exp_f32_e32 v60, v60
	v_exp_f32_e32 v61, v61
	v_exp_f32_e32 v62, v62
	v_exp_f32_e32 v63, v63
	v_exp_f32_e32 v64, v64
	v_exp_f32_e32 v65, v65
	v_pk_add_f32 v[58:59], v[58:59], v[216:217] op_sel_hi:[1,0]
	v_pk_add_f32 v[60:61], v[60:61], v[216:217] op_sel_hi:[1,0]
	v_pk_add_f32 v[62:63], v[62:63], v[216:217] op_sel_hi:[1,0]
	v_pk_add_f32 v[64:65], v[64:65], v[216:217] op_sel_hi:[1,0]
	v_rcp_f32_e32 v58, v58
	v_rcp_f32_e32 v59, v59
	v_rcp_f32_e32 v60, v60
	v_rcp_f32_e32 v61, v61
	v_rcp_f32_e32 v62, v62
	v_rcp_f32_e32 v63, v63
	v_rcp_f32_e32 v64, v64
	v_rcp_f32_e32 v65, v65
	v_pk_mul_f32 v[58:59], v[42:43], v[58:59]
	v_pk_mul_f32 v[60:61], v[44:45], v[60:61]
	v_pk_mul_f32 v[62:63], v[34:35], v[62:63]
	v_pk_mul_f32 v[64:65], v[36:37], v[64:65]
	v_pk_mul_f32 v[58:59], v[46:47], v[58:59]
	v_pk_mul_f32 v[60:61], v[48:49], v[60:61]
	v_pk_mul_f32 v[62:63], v[38:39], v[62:63]
	v_pk_mul_f32 v[64:65], v[40:41], v[64:65]
	v_mad_i64_i32 v[38:39], s[56:57], v150, s85, v[144:145]
	v_cvt_pk_bf16_f32 v34, v58, v59
	v_cvt_pk_bf16_f32 v35, v60, v61
	v_cvt_pk_bf16_f32 v36, v62, v63
	v_cvt_pk_bf16_f32 v37, v64, v65
	global_store_dwordx4 v[38:39], v[34:37], off
	v_pk_mul_f32 v[26:27], v[26:27], v[148:149] op_sel_hi:[1,0]
; #define PG8_BAR __builtin_amdgcn_s_barrier()
; __device__ __forceinline__ unsigned pk2(float lo, float hi) { return pg8::cvt_pk_bf16(lo, hi); }
; template <class Epi, class Sched, bool ALIGN_EPI = false, bool SP2 = false>
; __device__ __forceinline__ void gemm_phase(PG8_LAS unsigned char* lds, const Gemm g, const Sched& S, const Epi& E) {
;     ...
;         if constexpr (ALIGN_EPI) { if (wr == 0) PG8_BAR; }
;         if constexpr (!Epi::AFTER_DRAIN) { E(acc, cur, wr, wc, fr, fq); S.done(cur); }
;         if (!has_next) break;
; #pragma unroll
;         for (int a = 0; a < 2; ++a)
; #pragma unroll
;             for (int b = 0; b < 2; ++b)
; #pragma unroll
;                 for (int m = 0; m < 4; ++m)
; #pragma unroll
;                     for (int n = 0; n < 2; ++n) acc[a][b][m][n] = (f32x4){0.f, 0.f, 0.f, 0.f};
;         cur = nxt; cA = nA; cB = nB; ++ui;
;         if constexpr (ALIGN_EPI) { if (wr == 1) PG8_BAR; }
;     __device__ __forceinline__ void operator()(const f32x4 (&acc)[2][2][4][2], const Unit& u, int wr, int wc, int fr, int fq) const {
;     ...
; #pragma unroll
;         for (int ai = 0; ai < 2; ++ai)
; #pragma unroll
;             for (int m = 0; m < 4; ++m) {
;                 bf16_t* rowp = O + (size_t)(row0 + ai * 128 + m * 16) * FF + col0;
;                 const float rs = rsv[ai][m];
;                 float v[8];
; #pragma unroll
;                 for (int n = 0; n < 2; ++n)
; #pragma unroll
;                     for (int j = 0; j < 4; ++j) { const float g = acc[ai][0][m][n][j] * rs, up = acc[ai][1][m][n][j] * rs; v[n * 4 + j] = g * __builtin_amdgcn_rcpf(1.0f + __expf(-g)) * up; }
;                 u32x4v w; w.x = pk2(v[0], v[1]); w.y = pk2(v[2], v[3]); w.z = pk2(v[4], v[5]); w.w = pk2(v[6], v[7]);
;                 *(u32x4v*)rowp = w;
	v_pk_mul_f32 v[28:29], v[28:29], v[148:149] op_sel_hi:[1,0]
	v_pk_mul_f32 v[18:19], v[18:19], v[148:149] op_sel_hi:[1,0]
	v_pk_mul_f32 v[20:21], v[20:21], v[148:149] op_sel_hi:[1,0]
	v_pk_mul_f32 v[42:43], v[26:27], v[214:215] op_sel_hi:[1,0]
	v_pk_mul_f32 v[44:45], v[28:29], v[214:215] op_sel_hi:[1,0]
	v_pk_mul_f32 v[46:47], v[18:19], v[214:215] op_sel_hi:[1,0]
	v_pk_mul_f32 v[48:49], v[20:21], v[214:215] op_sel_hi:[1,0]
	v_pk_mul_f32 v[30:31], v[30:31], v[148:149] op_sel_hi:[1,0]
	v_pk_mul_f32 v[32:33], v[32:33], v[148:149] op_sel_hi:[1,0]
	v_pk_mul_f32 v[22:23], v[22:23], v[148:149] op_sel_hi:[1,0]
	v_pk_mul_f32 v[24:25], v[24:25], v[148:149] op_sel_hi:[1,0]
	v_exp_f32_e32 v42, v42
	v_exp_f32_e32 v43, v43
	v_exp_f32_e32 v44, v44
	v_exp_f32_e32 v45, v45
	v_exp_f32_e32 v46, v46
	v_exp_f32_e32 v47, v47
	v_exp_f32_e32 v48, v48
	v_exp_f32_e32 v49, v49
	v_pk_add_f32 v[42:43], v[42:43], v[216:217] op_sel_hi:[1,0]
	v_pk_add_f32 v[44:45], v[44:45], v[216:217] op_sel_hi:[1,0]
	v_pk_add_f32 v[46:47], v[46:47], v[216:217] op_sel_hi:[1,0]
	v_pk_add_f32 v[48:49], v[48:49], v[216:217] op_sel_hi:[1,0]
	v_rcp_f32_e32 v42, v42
	v_rcp_f32_e32 v43, v43
	v_rcp_f32_e32 v44, v44
	v_rcp_f32_e32 v45, v45
	v_rcp_f32_e32 v46, v46
	v_rcp_f32_e32 v47, v47
	v_rcp_f32_e32 v48, v48
	v_rcp_f32_e32 v49, v49
	v_pk_mul_f32 v[42:43], v[26:27], v[42:43]
	v_pk_mul_f32 v[44:45], v[28:29], v[44:45]
	v_pk_mul_f32 v[46:47], v[18:19], v[46:47]
	v_pk_mul_f32 v[48:49], v[20:21], v[48:49]
	v_pk_mul_f32 v[42:43], v[30:31], v[42:43]
	v_pk_mul_f32 v[44:45], v[32:33], v[44:45]
	v_pk_mul_f32 v[46:47], v[22:23], v[46:47]
	v_pk_mul_f32 v[48:49], v[24:25], v[48:49]
	v_mad_i64_i32 v[22:23], s[56:57], v142, s85, v[144:145]
	v_cvt_pk_bf16_f32 v18, v42, v43
	v_cvt_pk_bf16_f32 v19, v44, v45
	v_cvt_pk_bf16_f32 v20, v46, v47
	v_cvt_pk_bf16_f32 v21, v48, v49
	global_store_dwordx4 v[22:23], v[18:21], off
	v_pk_mul_f32 v[10:11], v[10:11], v[146:147] op_sel_hi:[1,0]
	v_pk_mul_f32 v[12:13], v[12:13], v[146:147] op_sel_hi:[1,0]
	v_pk_mul_f32 v[6:7], v[6:7], v[146:147] op_sel_hi:[1,0]
	v_pk_mul_f32 v[8:9], v[8:9], v[146:147] op_sel_hi:[1,0]
	v_pk_mul_f32 v[26:27], v[10:11], v[214:215] op_sel_hi:[1,0]
	v_pk_mul_f32 v[28:29], v[12:13], v[214:215] op_sel_hi:[1,0]
	v_pk_mul_f32 v[30:31], v[6:7], v[214:215] op_sel_hi:[1,0]
	v_pk_mul_f32 v[32:33], v[8:9], v[214:215] op_sel_hi:[1,0]
	v_pk_mul_f32 v[14:15], v[14:15], v[146:147] op_sel_hi:[1,0]
	v_pk_mul_f32 v[16:17], v[16:17], v[146:147] op_sel_hi:[1,0]
	v_pk_mul_f32 v[2:3], v[2:3], v[146:147] op_sel_hi:[1,0]
	v_pk_mul_f32 v[4:5], v[4:5], v[146:147] op_sel_hi:[1,0]
	v_exp_f32_e32 v26, v26
	v_exp_f32_e32 v27, v27
	v_exp_f32_e32 v28, v28
	v_exp_f32_e32 v29, v29
	v_exp_f32_e32 v30, v30
	v_exp_f32_e32 v31, v31
	v_exp_f32_e32 v32, v32
	v_exp_f32_e32 v33, v33
	v_pk_add_f32 v[26:27], v[26:27], v[216:217] op_sel_hi:[1,0]
	v_pk_add_f32 v[28:29], v[28:29], v[216:217] op_sel_hi:[1,0]
	v_pk_add_f32 v[30:31], v[30:31], v[216:217] op_sel_hi:[1,0]
	v_pk_add_f32 v[32:33], v[32:33], v[216:217] op_sel_hi:[1,0]
	v_rcp_f32_e32 v26, v26
	v_rcp_f32_e32 v27, v27
	v_rcp_f32_e32 v28, v28
	v_rcp_f32_e32 v29, v29
	v_rcp_f32_e32 v30, v30
	v_rcp_f32_e32 v31, v31
	v_rcp_f32_e32 v32, v32
	v_rcp_f32_e32 v33, v33
	v_pk_mul_f32 v[26:27], v[10:11], v[26:27]
	v_pk_mul_f32 v[28:29], v[12:13], v[28:29]
	v_pk_mul_f32 v[30:31], v[6:7], v[30:31]
	v_pk_mul_f32 v[32:33], v[8:9], v[32:33]
	v_pk_mul_f32 v[26:27], v[14:15], v[26:27]
	v_pk_mul_f32 v[28:29], v[16:17], v[28:29]
	v_pk_mul_f32 v[30:31], v[2:3], v[30:31]
	v_pk_mul_f32 v[32:33], v[4:5], v[32:33]
	v_mad_i64_i32 v[6:7], s[56:57], v140, s85, v[144:145]
	v_cvt_pk_bf16_f32 v2, v26, v27
	v_cvt_pk_bf16_f32 v3, v28, v29
	v_cvt_pk_bf16_f32 v4, v30, v31
	v_cvt_pk_bf16_f32 v5, v32, v33
	global_store_dwordx4 v[6:7], v[2:5], off
	s_cbranch_vccnz .LBB0_309
	s_andn2_b64 vcc, exec, s[38:39]
	s_cbranch_vccnz .LBB0_308
	s_barrier
	s_branch .LBB0_308

; __device__ __forceinline__ unsigned pk2(float lo, float hi) { return pg8::cvt_pk_bf16(lo, hi); }
;     __device__ __forceinline__ void operator()(const f32x4 (&acc)[2][2][4][2], const Unit& u, int wr, int wc, int fr, int fq) const {
;     ...
;             for (int m = 0; m < 4; ++m) pp[ai][m] = *(const f32x4*)(rss + (size_t)(row0 + ai * 128 + m * 16) * 4);
; #pragma unroll
;           for (int ai = 0; ai < 2; ++ai)
; #pragma unroll
;             for (int m = 0; m < 4; ++m) rsv[ai][m] = __builtin_amdgcn_rsqf(((pp[ai][m][0] + pp[ai][m][1]) + (pp[ai][m][2] + pp[ai][m][3])) * (1.0f / D) + EPS); }
; #pragma unroll
;         for (int ai = 0; ai < 2; ++ai)
; #pragma unroll
;             for (int m = 0; m < 4; ++m) {
;                 bf16_t* rowp = O + (size_t)(row0 + ai * 128 + m * 16) * FF + col0;
;                 const float rs = rsv[ai][m];
;                 float v[8];
; #pragma unroll
;                 for (int n = 0; n < 2; ++n)
; #pragma unroll
;                     for (int j = 0; j < 4; ++j) { const float g = acc[ai][0][m][n][j] * rs, up = acc[ai][1][m][n][j] * rs; v[n * 4 + j] = g * __builtin_amdgcn_rcpf(1.0f + __expf(-g)) * up; }
;                 u32x4v w; w.x = pk2(v[0], v[1]); w.y = pk2(v[2], v[3]); w.z = pk2(v[4], v[5]); w.w = pk2(v[6], v[7]);
;                 *(u32x4v*)rowp = w;
.LBB0_1195:
	v_readlane_b32 s68, v251, 4
	v_readlane_b32 s60, v250, 28
	v_lshl_add_u32 v178, s58, 8, v147
	v_readlane_b32 s69, v251, 5
	v_readlane_b32 s61, v250, 29
	v_ashrrev_i32_e32 v179, 31, v178
	v_or_b32_e32 v174, 16, v178
	v_lshl_add_u64 v[140:141], v[178:179], 4, s[60:61]
	global_load_dwordx4 v[180:183], v[140:141], off
	v_ashrrev_i32_e32 v175, 31, v174
	v_or_b32_e32 v170, 32, v178
	v_lshl_add_u64 v[140:141], v[174:175], 4, s[60:61]
	v_ashrrev_i32_e32 v171, 31, v170
	v_or_b32_e32 v166, 48, v178
	global_load_dwordx4 v[184:187], v[140:141], off
	v_lshl_add_u64 v[140:141], v[170:171], 4, s[60:61]
	v_ashrrev_i32_e32 v167, 31, v166
	v_add_u32_e32 v154, 0x80, v178
	global_load_dwordx4 v[188:191], v[140:141], off
	v_lshl_add_u64 v[140:141], v[166:167], 4, s[60:61]
	v_ashrrev_i32_e32 v155, 31, v154
	v_add_u32_e32 v150, 0x90, v178
	global_load_dwordx4 v[192:195], v[140:141], off
	v_lshl_add_u64 v[140:141], v[154:155], 4, s[60:61]
	v_ashrrev_i32_e32 v151, 31, v150
	v_add_u32_e32 v142, 0xa0, v178
	global_load_dwordx4 v[196:199], v[140:141], off
	v_lshl_add_u64 v[140:141], v[150:151], 4, s[60:61]
	v_ashrrev_i32_e32 v143, 31, v142
	global_load_dwordx4 v[200:203], v[140:141], off
	v_lshl_add_u64 v[140:141], v[142:143], 4, s[60:61]
	global_load_dwordx4 v[204:207], v[140:141], off
	v_add_u32_e32 v140, 0xb0, v178
	v_ashrrev_i32_e32 v141, 31, v140
	v_lshl_add_u64 v[144:145], v[140:141], 4, s[60:61]
	global_load_dwordx4 v[210:213], v[144:145], off
	s_and_b64 vcc, exec, s[40:41]
	s_waitcnt vmcnt(0) lgkmcnt(0)
	v_add_f32_e32 v180, v181, v180
	v_add_f32_e32 v184, v185, v184
	v_add_f32_e32 v188, v189, v188
	v_add_f32_e32 v192, v193, v192
	v_add_f32_e32 v196, v197, v196
	v_add_f32_e32 v200, v201, v200
	v_add_f32_e32 v204, v205, v204
	v_add_f32_e32 v210, v211, v210
	v_add_f32_e32 v182, v182, v183
	v_add_f32_e32 v186, v186, v187
	v_add_f32_e32 v190, v190, v191
	v_add_f32_e32 v194, v194, v195
	v_add_f32_e32 v198, v198, v199
	v_add_f32_e32 v202, v202, v203
	v_add_f32_e32 v206, v206, v207
	v_add_f32_e32 v212, v212, v213
	v_add_f32_e32 v180, v180, v182
	v_add_f32_e32 v184, v184, v186
	v_add_f32_e32 v188, v188, v190
	v_add_f32_e32 v192, v192, v194
	v_add_f32_e32 v196, v196, v198
	v_add_f32_e32 v200, v200, v202
	v_add_f32_e32 v204, v204, v206
	v_add_f32_e32 v210, v210, v212
	v_fmamk_f32 v180, v180, 0x3a800000, v159
	v_fmamk_f32 v184, v184, 0x3a800000, v159
	v_fmamk_f32 v188, v188, 0x3a800000, v159
	v_fmamk_f32 v192, v192, 0x3a800000, v159
	v_fmamk_f32 v196, v196, 0x3a800000, v159
	v_fmamk_f32 v200, v200, 0x3a800000, v159
	v_fmamk_f32 v204, v204, 0x3a800000, v159
	v_fmamk_f32 v210, v210, 0x3a800000, v159
	v_rsq_f32_e32 v180, v180
	v_rsq_f32_e32 v176, v184
	v_rsq_f32_e32 v172, v188
	v_rsq_f32_e32 v168, v192
	v_rsq_f32_e32 v156, v196
	v_rsq_f32_e32 v152, v200
	v_rsq_f32_e32 v148, v204
	v_rsq_f32_e32 v146, v210
	v_mov_b32_e32 v210, 0xbfb8aa3b
	v_mov_b32_e32 v212, 1.0
	v_lshl_or_b32 v144, s57, 7, v153
	v_ashrrev_i32_e32 v145, 31, v144
	v_lshl_add_u64 v[144:145], v[144:145], 1, s[68:69]
	s_mov_b64 s[68:69], -1
	v_pk_mul_f32 v[122:123], v[122:123], v[180:181] op_sel_hi:[1,0]
	v_pk_mul_f32 v[124:125], v[124:125], v[180:181] op_sel_hi:[1,0]
	v_pk_mul_f32 v[114:115], v[114:115], v[180:181] op_sel_hi:[1,0]
	v_pk_mul_f32 v[116:117], v[116:117], v[180:181] op_sel_hi:[1,0]
	v_pk_mul_f32 v[184:185], v[122:123], v[210:211] op_sel_hi:[1,0]
	v_pk_mul_f32 v[186:187], v[124:125], v[210:211] op_sel_hi:[1,0]
	v_pk_mul_f32 v[188:189], v[114:115], v[210:211] op_sel_hi:[1,0]
	v_pk_mul_f32 v[190:191], v[116:117], v[210:211] op_sel_hi:[1,0]
	v_pk_mul_f32 v[126:127], v[126:127], v[180:181] op_sel_hi:[1,0]
	v_pk_mul_f32 v[128:129], v[128:129], v[180:181] op_sel_hi:[1,0]
	v_pk_mul_f32 v[118:119], v[118:119], v[180:181] op_sel_hi:[1,0]
	v_pk_mul_f32 v[120:121], v[120:121], v[180:181] op_sel_hi:[1,0]
	v_exp_f32_e32 v184, v184
	v_exp_f32_e32 v185, v185
	v_exp_f32_e32 v186, v186
	v_exp_f32_e32 v187, v187
	v_exp_f32_e32 v188, v188
	v_exp_f32_e32 v189, v189
	v_exp_f32_e32 v190, v190
	v_exp_f32_e32 v191, v191
	v_pk_add_f32 v[184:185], v[184:185], v[212:213] op_sel_hi:[1,0]
	v_pk_add_f32 v[186:187], v[186:187], v[212:213] op_sel_hi:[1,0]
	v_pk_add_f32 v[188:189], v[188:189], v[212:213] op_sel_hi:[1,0]
	v_pk_add_f32 v[190:191], v[190:191], v[212:213] op_sel_hi:[1,0]
	v_rcp_f32_e32 v184, v184
	v_rcp_f32_e32 v185, v185
	v_rcp_f32_e32 v186, v186
	v_rcp_f32_e32 v187, v187
	v_rcp_f32_e32 v188, v188
	v_rcp_f32_e32 v189, v189
	v_rcp_f32_e32 v190, v190
	v_rcp_f32_e32 v191, v191
	v_pk_mul_f32 v[184:185], v[122:123], v[184:185]
	v_pk_mul_f32 v[186:187], v[124:125], v[186:187]
	v_pk_mul_f32 v[188:189], v[114:115], v[188:189]
	v_pk_mul_f32 v[190:191], v[116:117], v[190:191]
	v_pk_mul_f32 v[184:185], v[126:127], v[184:185]
	v_pk_mul_f32 v[186:187], v[128:129], v[186:187]
	v_pk_mul_f32 v[188:189], v[118:119], v[188:189]
	v_pk_mul_f32 v[190:191], v[120:121], v[190:191]
	v_mad_i64_i32 v[118:119], s[58:59], v178, s85, v[144:145]
	v_cvt_pk_bf16_f32 v114, v184, v185
	v_cvt_pk_bf16_f32 v115, v186, v187
	v_cvt_pk_bf16_f32 v116, v188, v189
	v_cvt_pk_bf16_f32 v117, v190, v191
	global_store_dwordx4 v[118:119], v[114:117], off
	v_pk_mul_f32 v[106:107], v[106:107], v[176:177] op_sel_hi:[1,0]
	v_pk_mul_f32 v[108:109], v[108:109], v[176:177] op_sel_hi:[1,0]
	v_pk_mul_f32 v[98:99], v[98:99], v[176:177] op_sel_hi:[1,0]
	v_pk_mul_f32 v[100:101], v[100:101], v[176:177] op_sel_hi:[1,0]
	v_pk_mul_f32 v[122:123], v[106:107], v[210:211] op_sel_hi:[1,0]
	v_pk_mul_f32 v[124:125], v[108:109], v[210:211] op_sel_hi:[1,0]
	v_pk_mul_f32 v[126:127], v[98:99], v[210:211] op_sel_hi:[1,0]
	v_pk_mul_f32 v[128:129], v[100:101], v[210:211] op_sel_hi:[1,0]
; __device__ __forceinline__ unsigned pk2(float lo, float hi) { return pg8::cvt_pk_bf16(lo, hi); }
;     __device__ __forceinline__ void operator()(const f32x4 (&acc)[2][2][4][2], const Unit& u, int wr, int wc, int fr, int fq) const {
;     ...
;         for (int ai = 0; ai < 2; ++ai)
; #pragma unroll
;             for (int m = 0; m < 4; ++m) {
;                 bf16_t* rowp = O + (size_t)(row0 + ai * 128 + m * 16) * FF + col0;
;                 const float rs = rsv[ai][m];
;                 float v[8];
; #pragma unroll
;                 for (int n = 0; n < 2; ++n)
; #pragma unroll
;                     for (int j = 0; j < 4; ++j) { const float g = acc[ai][0][m][n][j] * rs, up = acc[ai][1][m][n][j] * rs; v[n * 4 + j] = g * __builtin_amdgcn_rcpf(1.0f + __expf(-g)) * up; }
;                 u32x4v w; w.x = pk2(v[0], v[1]); w.y = pk2(v[2], v[3]); w.z = pk2(v[4], v[5]); w.w = pk2(v[6], v[7]);
;                 *(u32x4v*)rowp = w;
	v_pk_mul_f32 v[110:111], v[110:111], v[176:177] op_sel_hi:[1,0]
	v_pk_mul_f32 v[112:113], v[112:113], v[176:177] op_sel_hi:[1,0]
	v_pk_mul_f32 v[102:103], v[102:103], v[176:177] op_sel_hi:[1,0]
	v_pk_mul_f32 v[104:105], v[104:105], v[176:177] op_sel_hi:[1,0]
	v_exp_f32_e32 v122, v122
	v_exp_f32_e32 v123, v123
	v_exp_f32_e32 v124, v124
	v_exp_f32_e32 v125, v125
	v_exp_f32_e32 v126, v126
	v_exp_f32_e32 v127, v127
	v_exp_f32_e32 v128, v128
	v_exp_f32_e32 v129, v129
	v_pk_add_f32 v[122:123], v[122:123], v[212:213] op_sel_hi:[1,0]
	v_pk_add_f32 v[124:125], v[124:125], v[212:213] op_sel_hi:[1,0]
	v_pk_add_f32 v[126:127], v[126:127], v[212:213] op_sel_hi:[1,0]
	v_pk_add_f32 v[128:129], v[128:129], v[212:213] op_sel_hi:[1,0]
	v_rcp_f32_e32 v122, v122
	v_rcp_f32_e32 v123, v123
	v_rcp_f32_e32 v124, v124
	v_rcp_f32_e32 v125, v125
	v_rcp_f32_e32 v126, v126
	v_rcp_f32_e32 v127, v127
	v_rcp_f32_e32 v128, v128
	v_rcp_f32_e32 v129, v129
	v_pk_mul_f32 v[122:123], v[106:107], v[122:123]
	v_pk_mul_f32 v[124:125], v[108:109], v[124:125]
	v_pk_mul_f32 v[126:127], v[98:99], v[126:127]
	v_pk_mul_f32 v[128:129], v[100:101], v[128:129]
	v_pk_mul_f32 v[122:123], v[110:111], v[122:123]
	v_pk_mul_f32 v[124:125], v[112:113], v[124:125]
	v_pk_mul_f32 v[126:127], v[102:103], v[126:127]
	v_pk_mul_f32 v[128:129], v[104:105], v[128:129]
	v_mad_i64_i32 v[102:103], s[58:59], v174, s85, v[144:145]
	v_cvt_pk_bf16_f32 v98, v122, v123
	v_cvt_pk_bf16_f32 v99, v124, v125
	v_cvt_pk_bf16_f32 v100, v126, v127
	v_cvt_pk_bf16_f32 v101, v128, v129
	global_store_dwordx4 v[102:103], v[98:101], off
	v_pk_mul_f32 v[90:91], v[90:91], v[172:173] op_sel_hi:[1,0]
	v_pk_mul_f32 v[92:93], v[92:93], v[172:173] op_sel_hi:[1,0]
	v_pk_mul_f32 v[82:83], v[82:83], v[172:173] op_sel_hi:[1,0]
	v_pk_mul_f32 v[84:85], v[84:85], v[172:173] op_sel_hi:[1,0]
	v_pk_mul_f32 v[106:107], v[90:91], v[210:211] op_sel_hi:[1,0]
	v_pk_mul_f32 v[108:109], v[92:93], v[210:211] op_sel_hi:[1,0]
	v_pk_mul_f32 v[110:111], v[82:83], v[210:211] op_sel_hi:[1,0]
	v_pk_mul_f32 v[112:113], v[84:85], v[210:211] op_sel_hi:[1,0]
	v_pk_mul_f32 v[94:95], v[94:95], v[172:173] op_sel_hi:[1,0]
	v_pk_mul_f32 v[96:97], v[96:97], v[172:173] op_sel_hi:[1,0]
	v_pk_mul_f32 v[86:87], v[86:87], v[172:173] op_sel_hi:[1,0]
	v_pk_mul_f32 v[88:89], v[88:89], v[172:173] op_sel_hi:[1,0]
	v_exp_f32_e32 v106, v106
	v_exp_f32_e32 v107, v107
	v_exp_f32_e32 v108, v108
	v_exp_f32_e32 v109, v109
	v_exp_f32_e32 v110, v110
	v_exp_f32_e32 v111, v111
	v_exp_f32_e32 v112, v112
	v_exp_f32_e32 v113, v113
	v_pk_add_f32 v[106:107], v[106:107], v[212:213] op_sel_hi:[1,0]
	v_pk_add_f32 v[108:109], v[108:109], v[212:213] op_sel_hi:[1,0]
	v_pk_add_f32 v[110:111], v[110:111], v[212:213] op_sel_hi:[1,0]
	v_pk_add_f32 v[112:113], v[112:113], v[212:213] op_sel_hi:[1,0]
	v_rcp_f32_e32 v106, v106
	v_rcp_f32_e32 v107, v107
	v_rcp_f32_e32 v108, v108
	v_rcp_f32_e32 v109, v109
	v_rcp_f32_e32 v110, v110
	v_rcp_f32_e32 v111, v111
	v_rcp_f32_e32 v112, v112
	v_rcp_f32_e32 v113, v113
	v_pk_mul_f32 v[106:107], v[90:91], v[106:107]
	v_pk_mul_f32 v[108:109], v[92:93], v[108:109]
	v_pk_mul_f32 v[110:111], v[82:83], v[110:111]
	v_pk_mul_f32 v[112:113], v[84:85], v[112:113]
	v_pk_mul_f32 v[106:107], v[94:95], v[106:107]
	v_pk_mul_f32 v[108:109], v[96:97], v[108:109]
	v_pk_mul_f32 v[110:111], v[86:87], v[110:111]
	v_pk_mul_f32 v[112:113], v[88:89], v[112:113]
	v_mad_i64_i32 v[86:87], s[58:59], v170, s85, v[144:145]
	v_cvt_pk_bf16_f32 v82, v106, v107
	v_cvt_pk_bf16_f32 v83, v108, v109
	v_cvt_pk_bf16_f32 v84, v110, v111
	v_cvt_pk_bf16_f32 v85, v112, v113
	global_store_dwordx4 v[86:87], v[82:85], off
	v_pk_mul_f32 v[74:75], v[74:75], v[168:169] op_sel_hi:[1,0]
	v_pk_mul_f32 v[76:77], v[76:77], v[168:169] op_sel_hi:[1,0]
	v_pk_mul_f32 v[66:67], v[66:67], v[168:169] op_sel_hi:[1,0]
	v_pk_mul_f32 v[68:69], v[68:69], v[168:169] op_sel_hi:[1,0]
	v_pk_mul_f32 v[90:91], v[74:75], v[210:211] op_sel_hi:[1,0]
	v_pk_mul_f32 v[92:93], v[76:77], v[210:211] op_sel_hi:[1,0]
	v_pk_mul_f32 v[94:95], v[66:67], v[210:211] op_sel_hi:[1,0]
	v_pk_mul_f32 v[96:97], v[68:69], v[210:211] op_sel_hi:[1,0]
	v_pk_mul_f32 v[78:79], v[78:79], v[168:169] op_sel_hi:[1,0]
	v_pk_mul_f32 v[80:81], v[80:81], v[168:169] op_sel_hi:[1,0]
	v_pk_mul_f32 v[70:71], v[70:71], v[168:169] op_sel_hi:[1,0]
	v_pk_mul_f32 v[72:73], v[72:73], v[168:169] op_sel_hi:[1,0]
	v_exp_f32_e32 v90, v90
	v_exp_f32_e32 v91, v91
	v_exp_f32_e32 v92, v92
	v_exp_f32_e32 v93, v93
	v_exp_f32_e32 v94, v94
	v_exp_f32_e32 v95, v95
	v_exp_f32_e32 v96, v96
	v_exp_f32_e32 v97, v97
	v_pk_add_f32 v[90:91], v[90:91], v[212:213] op_sel_hi:[1,0]
	v_pk_add_f32 v[92:93], v[92:93], v[212:213] op_sel_hi:[1,0]
	v_pk_add_f32 v[94:95], v[94:95], v[212:213] op_sel_hi:[1,0]
	v_pk_add_f32 v[96:97], v[96:97], v[212:213] op_sel_hi:[1,0]
	v_rcp_f32_e32 v90, v90
	v_rcp_f32_e32 v91, v91
	v_rcp_f32_e32 v92, v92
	v_rcp_f32_e32 v93, v93
	v_rcp_f32_e32 v94, v94
	v_rcp_f32_e32 v95, v95
	v_rcp_f32_e32 v96, v96
	v_rcp_f32_e32 v97, v97
	v_pk_mul_f32 v[90:91], v[74:75], v[90:91]
	v_pk_mul_f32 v[92:93], v[76:77], v[92:93]
	v_pk_mul_f32 v[94:95], v[66:67], v[94:95]
	v_pk_mul_f32 v[96:97], v[68:69], v[96:97]
	v_pk_mul_f32 v[90:91], v[78:79], v[90:91]
	v_pk_mul_f32 v[92:93], v[80:81], v[92:93]
	v_pk_mul_f32 v[94:95], v[70:71], v[94:95]
	v_pk_mul_f32 v[96:97], v[72:73], v[96:97]
	v_mad_i64_i32 v[70:71], s[58:59], v166, s85, v[144:145]
	v_cvt_pk_bf16_f32 v66, v90, v91
	v_cvt_pk_bf16_f32 v67, v92, v93
	v_cvt_pk_bf16_f32 v68, v94, v95
	v_cvt_pk_bf16_f32 v69, v96, v97
	global_store_dwordx4 v[70:71], v[66:69], off
	v_pk_mul_f32 v[58:59], v[58:59], v[156:157] op_sel_hi:[1,0]
; __device__ __forceinline__ unsigned pk2(float lo, float hi) { return pg8::cvt_pk_bf16(lo, hi); }
;     __device__ __forceinline__ void operator()(const f32x4 (&acc)[2][2][4][2], const Unit& u, int wr, int wc, int fr, int fq) const {
;     ...
;         for (int ai = 0; ai < 2; ++ai)
; #pragma unroll
;             for (int m = 0; m < 4; ++m) {
;                 bf16_t* rowp = O + (size_t)(row0 + ai * 128 + m * 16) * FF + col0;
;                 const float rs = rsv[ai][m];
;                 float v[8];
; #pragma unroll
;                 for (int n = 0; n < 2; ++n)
; #pragma unroll
;                     for (int j = 0; j < 4; ++j) { const float g = acc[ai][0][m][n][j] * rs, up = acc[ai][1][m][n][j] * rs; v[n * 4 + j] = g * __builtin_amdgcn_rcpf(1.0f + __expf(-g)) * up; }
;                 u32x4v w; w.x = pk2(v[0], v[1]); w.y = pk2(v[2], v[3]); w.z = pk2(v[4], v[5]); w.w = pk2(v[6], v[7]);
;                 *(u32x4v*)rowp = w;
	v_pk_mul_f32 v[60:61], v[60:61], v[156:157] op_sel_hi:[1,0]
	v_pk_mul_f32 v[50:51], v[50:51], v[156:157] op_sel_hi:[1,0]
	v_pk_mul_f32 v[52:53], v[52:53], v[156:157] op_sel_hi:[1,0]
	v_pk_mul_f32 v[74:75], v[58:59], v[210:211] op_sel_hi:[1,0]
	v_pk_mul_f32 v[76:77], v[60:61], v[210:211] op_sel_hi:[1,0]
	v_pk_mul_f32 v[78:79], v[50:51], v[210:211] op_sel_hi:[1,0]
	v_pk_mul_f32 v[80:81], v[52:53], v[210:211] op_sel_hi:[1,0]
	v_pk_mul_f32 v[62:63], v[62:63], v[156:157] op_sel_hi:[1,0]
	v_pk_mul_f32 v[64:65], v[64:65], v[156:157] op_sel_hi:[1,0]
	v_pk_mul_f32 v[54:55], v[54:55], v[156:157] op_sel_hi:[1,0]
	v_pk_mul_f32 v[56:57], v[56:57], v[156:157] op_sel_hi:[1,0]
	v_exp_f32_e32 v74, v74
	v_exp_f32_e32 v75, v75
	v_exp_f32_e32 v76, v76
	v_exp_f32_e32 v77, v77
	v_exp_f32_e32 v78, v78
	v_exp_f32_e32 v79, v79
	v_exp_f32_e32 v80, v80
	v_exp_f32_e32 v81, v81
	v_pk_add_f32 v[74:75], v[74:75], v[212:213] op_sel_hi:[1,0]
	v_pk_add_f32 v[76:77], v[76:77], v[212:213] op_sel_hi:[1,0]
	v_pk_add_f32 v[78:79], v[78:79], v[212:213] op_sel_hi:[1,0]
	v_pk_add_f32 v[80:81], v[80:81], v[212:213] op_sel_hi:[1,0]
	v_rcp_f32_e32 v74, v74
	v_rcp_f32_e32 v75, v75
	v_rcp_f32_e32 v76, v76
	v_rcp_f32_e32 v77, v77
	v_rcp_f32_e32 v78, v78
	v_rcp_f32_e32 v79, v79
	v_rcp_f32_e32 v80, v80
	v_rcp_f32_e32 v81, v81
	v_pk_mul_f32 v[74:75], v[58:59], v[74:75]
	v_pk_mul_f32 v[76:77], v[60:61], v[76:77]
	v_pk_mul_f32 v[78:79], v[50:51], v[78:79]
	v_pk_mul_f32 v[80:81], v[52:53], v[80:81]
	v_pk_mul_f32 v[74:75], v[62:63], v[74:75]
	v_pk_mul_f32 v[76:77], v[64:65], v[76:77]
	v_pk_mul_f32 v[78:79], v[54:55], v[78:79]
	v_pk_mul_f32 v[80:81], v[56:57], v[80:81]
	v_mad_i64_i32 v[54:55], s[58:59], v154, s85, v[144:145]
	v_cvt_pk_bf16_f32 v50, v74, v75
	v_cvt_pk_bf16_f32 v51, v76, v77
	v_cvt_pk_bf16_f32 v52, v78, v79
	v_cvt_pk_bf16_f32 v53, v80, v81
	global_store_dwordx4 v[54:55], v[50:53], off
	v_pk_mul_f32 v[42:43], v[42:43], v[152:153] op_sel_hi:[1,0]
	v_pk_mul_f32 v[44:45], v[44:45], v[152:153] op_sel_hi:[1,0]
	v_pk_mul_f32 v[34:35], v[34:35], v[152:153] op_sel_hi:[1,0]
	v_pk_mul_f32 v[36:37], v[36:37], v[152:153] op_sel_hi:[1,0]
	v_pk_mul_f32 v[58:59], v[42:43], v[210:211] op_sel_hi:[1,0]
	v_pk_mul_f32 v[60:61], v[44:45], v[210:211] op_sel_hi:[1,0]
	v_pk_mul_f32 v[62:63], v[34:35], v[210:211] op_sel_hi:[1,0]
	v_pk_mul_f32 v[64:65], v[36:37], v[210:211] op_sel_hi:[1,0]
	v_pk_mul_f32 v[46:47], v[46:47], v[152:153] op_sel_hi:[1,0]
	v_pk_mul_f32 v[48:49], v[48:49], v[152:153] op_sel_hi:[1,0]
	v_pk_mul_f32 v[38:39], v[38:39], v[152:153] op_sel_hi:[1,0]
	v_pk_mul_f32 v[40:41], v[40:41], v[152:153] op_sel_hi:[1,0]
	v_exp_f32_e32 v58, v58
	v_exp_f32_e32 v59, v59
	v_exp_f32_e32 v60, v60
	v_exp_f32_e32 v61, v61
	v_exp_f32_e32 v62, v62
	v_exp_f32_e32 v63, v63
	v_exp_f32_e32 v64, v64
	v_exp_f32_e32 v65, v65
	v_pk_add_f32 v[58:59], v[58:59], v[212:213] op_sel_hi:[1,0]
	v_pk_add_f32 v[60:61], v[60:61], v[212:213] op_sel_hi:[1,0]
	v_pk_add_f32 v[62:63], v[62:63], v[212:213] op_sel_hi:[1,0]
	v_pk_add_f32 v[64:65], v[64:65], v[212:213] op_sel_hi:[1,0]
	v_rcp_f32_e32 v58, v58
	v_rcp_f32_e32 v59, v59
	v_rcp_f32_e32 v60, v60
	v_rcp_f32_e32 v61, v61
	v_rcp_f32_e32 v62, v62
	v_rcp_f32_e32 v63, v63
	v_rcp_f32_e32 v64, v64
	v_rcp_f32_e32 v65, v65
	v_pk_mul_f32 v[58:59], v[42:43], v[58:59]
	v_pk_mul_f32 v[60:61], v[44:45], v[60:61]
	v_pk_mul_f32 v[62:63], v[34:35], v[62:63]
	v_pk_mul_f32 v[64:65], v[36:37], v[64:65]
	v_pk_mul_f32 v[58:59], v[46:47], v[58:59]
	v_pk_mul_f32 v[60:61], v[48:49], v[60:61]
	v_pk_mul_f32 v[62:63], v[38:39], v[62:63]
	v_pk_mul_f32 v[64:65], v[40:41], v[64:65]
	v_mad_i64_i32 v[38:39], s[58:59], v150, s85, v[144:145]
	v_cvt_pk_bf16_f32 v34, v58, v59
	v_cvt_pk_bf16_f32 v35, v60, v61
	v_cvt_pk_bf16_f32 v36, v62, v63
	v_cvt_pk_bf16_f32 v37, v64, v65
	global_store_dwordx4 v[38:39], v[34:37], off
	v_pk_mul_f32 v[26:27], v[26:27], v[148:149] op_sel_hi:[1,0]
; __device__ __forceinline__ unsigned pk2(float lo, float hi) { return pg8::cvt_pk_bf16(lo, hi); }
;     __device__ __forceinline__ void operator()(const f32x4 (&acc)[2][2][4][2], const Unit& u, int wr, int wc, int fr, int fq) const {
;     ...
;         for (int ai = 0; ai < 2; ++ai)
; #pragma unroll
;             for (int m = 0; m < 4; ++m) {
;                 bf16_t* rowp = O + (size_t)(row0 + ai * 128 + m * 16) * FF + col0;
;                 const float rs = rsv[ai][m];
;                 float v[8];
; #pragma unroll
;                 for (int n = 0; n < 2; ++n)
; #pragma unroll
;                     for (int j = 0; j < 4; ++j) { const float g = acc[ai][0][m][n][j] * rs, up = acc[ai][1][m][n][j] * rs; v[n * 4 + j] = g * __builtin_amdgcn_rcpf(1.0f + __expf(-g)) * up; }
;                 u32x4v w; w.x = pk2(v[0], v[1]); w.y = pk2(v[2], v[3]); w.z = pk2(v[4], v[5]); w.w = pk2(v[6], v[7]);
;                 *(u32x4v*)rowp = w;
	v_pk_mul_f32 v[28:29], v[28:29], v[148:149] op_sel_hi:[1,0]
	v_pk_mul_f32 v[18:19], v[18:19], v[148:149] op_sel_hi:[1,0]
	v_pk_mul_f32 v[20:21], v[20:21], v[148:149] op_sel_hi:[1,0]
	v_pk_mul_f32 v[42:43], v[26:27], v[210:211] op_sel_hi:[1,0]
	v_pk_mul_f32 v[44:45], v[28:29], v[210:211] op_sel_hi:[1,0]
	v_pk_mul_f32 v[46:47], v[18:19], v[210:211] op_sel_hi:[1,0]
	v_pk_mul_f32 v[48:49], v[20:21], v[210:211] op_sel_hi:[1,0]
	v_pk_mul_f32 v[30:31], v[30:31], v[148:149] op_sel_hi:[1,0]
	v_pk_mul_f32 v[32:33], v[32:33], v[148:149] op_sel_hi:[1,0]
	v_pk_mul_f32 v[22:23], v[22:23], v[148:149] op_sel_hi:[1,0]
	v_pk_mul_f32 v[24:25], v[24:25], v[148:149] op_sel_hi:[1,0]
	v_exp_f32_e32 v42, v42
	v_exp_f32_e32 v43, v43
	v_exp_f32_e32 v44, v44
	v_exp_f32_e32 v45, v45
	v_exp_f32_e32 v46, v46
	v_exp_f32_e32 v47, v47
	v_exp_f32_e32 v48, v48
	v_exp_f32_e32 v49, v49
	v_pk_add_f32 v[42:43], v[42:43], v[212:213] op_sel_hi:[1,0]
	v_pk_add_f32 v[44:45], v[44:45], v[212:213] op_sel_hi:[1,0]
	v_pk_add_f32 v[46:47], v[46:47], v[212:213] op_sel_hi:[1,0]
	v_pk_add_f32 v[48:49], v[48:49], v[212:213] op_sel_hi:[1,0]
	v_rcp_f32_e32 v42, v42
	v_rcp_f32_e32 v43, v43
	v_rcp_f32_e32 v44, v44
	v_rcp_f32_e32 v45, v45
	v_rcp_f32_e32 v46, v46
	v_rcp_f32_e32 v47, v47
	v_rcp_f32_e32 v48, v48
	v_rcp_f32_e32 v49, v49
	v_pk_mul_f32 v[42:43], v[26:27], v[42:43]
	v_pk_mul_f32 v[44:45], v[28:29], v[44:45]
	v_pk_mul_f32 v[46:47], v[18:19], v[46:47]
	v_pk_mul_f32 v[48:49], v[20:21], v[48:49]
	v_pk_mul_f32 v[42:43], v[30:31], v[42:43]
	v_pk_mul_f32 v[44:45], v[32:33], v[44:45]
	v_pk_mul_f32 v[46:47], v[22:23], v[46:47]
	v_pk_mul_f32 v[48:49], v[24:25], v[48:49]
	v_mad_i64_i32 v[22:23], s[58:59], v142, s85, v[144:145]
	v_cvt_pk_bf16_f32 v18, v42, v43
	v_cvt_pk_bf16_f32 v19, v44, v45
	v_cvt_pk_bf16_f32 v20, v46, v47
	v_cvt_pk_bf16_f32 v21, v48, v49
	global_store_dwordx4 v[22:23], v[18:21], off
	v_pk_mul_f32 v[10:11], v[10:11], v[146:147] op_sel_hi:[1,0]
	v_pk_mul_f32 v[12:13], v[12:13], v[146:147] op_sel_hi:[1,0]
	v_pk_mul_f32 v[6:7], v[6:7], v[146:147] op_sel_hi:[1,0]
	v_pk_mul_f32 v[8:9], v[8:9], v[146:147] op_sel_hi:[1,0]
	v_pk_mul_f32 v[26:27], v[10:11], v[210:211] op_sel_hi:[1,0]
	v_pk_mul_f32 v[28:29], v[12:13], v[210:211] op_sel_hi:[1,0]
	v_pk_mul_f32 v[30:31], v[6:7], v[210:211] op_sel_hi:[1,0]
	v_pk_mul_f32 v[32:33], v[8:9], v[210:211] op_sel_hi:[1,0]
	v_pk_mul_f32 v[14:15], v[14:15], v[146:147] op_sel_hi:[1,0]
	v_pk_mul_f32 v[16:17], v[16:17], v[146:147] op_sel_hi:[1,0]
	v_pk_mul_f32 v[2:3], v[2:3], v[146:147] op_sel_hi:[1,0]
	v_pk_mul_f32 v[4:5], v[4:5], v[146:147] op_sel_hi:[1,0]
	v_exp_f32_e32 v26, v26
	v_exp_f32_e32 v27, v27
	v_exp_f32_e32 v28, v28
	v_exp_f32_e32 v29, v29
	v_exp_f32_e32 v30, v30
	v_exp_f32_e32 v31, v31
	v_exp_f32_e32 v32, v32
	v_exp_f32_e32 v33, v33
	v_pk_add_f32 v[26:27], v[26:27], v[212:213] op_sel_hi:[1,0]
	v_pk_add_f32 v[28:29], v[28:29], v[212:213] op_sel_hi:[1,0]
	v_pk_add_f32 v[30:31], v[30:31], v[212:213] op_sel_hi:[1,0]
	v_pk_add_f32 v[32:33], v[32:33], v[212:213] op_sel_hi:[1,0]
	v_rcp_f32_e32 v26, v26
	v_rcp_f32_e32 v27, v27
	v_rcp_f32_e32 v28, v28
	v_rcp_f32_e32 v29, v29
	v_rcp_f32_e32 v30, v30
	v_rcp_f32_e32 v31, v31
	v_rcp_f32_e32 v32, v32
	v_rcp_f32_e32 v33, v33
	v_pk_mul_f32 v[26:27], v[10:11], v[26:27]
	v_pk_mul_f32 v[28:29], v[12:13], v[28:29]
	v_pk_mul_f32 v[30:31], v[6:7], v[30:31]
	v_pk_mul_f32 v[32:33], v[8:9], v[32:33]
	v_pk_mul_f32 v[26:27], v[14:15], v[26:27]
	v_pk_mul_f32 v[28:29], v[16:17], v[28:29]
	v_pk_mul_f32 v[30:31], v[2:3], v[30:31]
	v_pk_mul_f32 v[32:33], v[4:5], v[32:33]
	v_mad_i64_i32 v[6:7], s[58:59], v140, s85, v[144:145]
	v_cvt_pk_bf16_f32 v2, v26, v27
	v_cvt_pk_bf16_f32 v3, v28, v29
	v_cvt_pk_bf16_f32 v4, v30, v31
	v_cvt_pk_bf16_f32 v5, v32, v33
	global_store_dwordx4 v[6:7], v[2:5], off
	s_cbranch_vccnz .LBB0_1182
	s_andn2_b64 vcc, exec, s[18:19]
	s_cbranch_vccnz .LBB0_1181
	s_barrier
	s_branch .LBB0_1181
